# P8 forget-logit pass: K-loop loads de-serialised (32 loads in flight, counted vmcnt) and bias/rowss loads hoisted above the loop
# speedup vs baseline: 1.0083x; 1.0083x over previous
; __device__ __forceinline__ void fl_phase(const bf16* H, const bf16* Wfl, const float* bfv, const float* rowss, const float* biasp, float* logf, int G) {
;     ...
;     for (int rb = blockIdx.x + G * wave; rb < M / 16; rb += G * NWAVES) {
;         const bf16* ap = H + (size_t)(16 * rb + li) * D + 8 * g; const bf16* bp = Wfl + (size_t)li * D + 8 * g;
;         f32x4 acc = (f32x4){0.f, 0.f, 0.f, 0.f};
; #pragma unroll 8
;         for (int ks = 0; ks < 32; ++ks) { const bf16x8 a = *(const bf16x8*)(ap + 32 * ks), b = *(const bf16x8*)(bp + 32 * ks);
;             acc = __builtin_amdgcn_mfma_f32_16x16x32_bf16(a, b, acc, 0, 0, 0); }
;         const int row = 16 * rb + 4 * g, bb = row >> 13, t = row & 8191; const float bias = bfv[li] + biasp[bb * 4352 + 4096 + li];
.LBB0_619:
	v_ashrrev_i32_e32 v15, 31, v14
	v_lshlrev_b64 v[0:1], 11, v[14:15]
	v_lshl_add_u64 v[4:5], v[12:13], 0, v[0:1]
	s_mov_b64 s[18:19], 0
	v_mov_b32_e32 v0, 0
	v_mov_b32_e32 v1, v9
	v_mov_b32_e32 v2, v9
	v_mov_b32_e32 v3, v9
	v_ashrrev_i32_e32 v192, 9, v44
	s_movk_i32 s98, 0x1100
	v_mad_i32_i24 v192, v192, s98, v46
	v_ashrrev_i32_e32 v193, 31, v192
	v_lshl_add_u64 v[192:193], v[192:193], 2, s[44:45]
	v_lshlrev_b32_e32 v194, 4, v44
	v_or_b32_e32 v194, v194, v47
	v_ashrrev_i32_e32 v195, 31, v194
	v_lshl_add_u64 v[194:195], v[194:195], 2, s[42:43]
	global_load_dword v186, v[10:11], off
	global_load_dword v187, v[192:193], off
	global_load_dwordx4 v[188:191], v[194:195], off
	v_add_co_u32_e32 v6, vcc, 0x1800000, v4
	s_nop 1
	v_addc_co_u32_e32 v7, vcc, 0, v5, vcc
	v_add_co_u32_e32 v28, vcc, 0x1200000, v16
	s_nop 1
	v_addc_co_u32_e32 v29, vcc, 0, v17, vcc
	global_load_dwordx4 v[58:61], v[6:7], off
	global_load_dwordx4 v[62:65], v[28:29], off
	global_load_dwordx4 v[66:69], v[6:7], off offset:64
	global_load_dwordx4 v[70:73], v[28:29], off offset:64
	global_load_dwordx4 v[74:77], v[6:7], off offset:128
	global_load_dwordx4 v[78:81], v[28:29], off offset:128
	global_load_dwordx4 v[82:85], v[6:7], off offset:192
	global_load_dwordx4 v[86:89], v[28:29], off offset:192
	global_load_dwordx4 v[90:93], v[6:7], off offset:256
	global_load_dwordx4 v[94:97], v[28:29], off offset:256
	global_load_dwordx4 v[98:101], v[6:7], off offset:320
	global_load_dwordx4 v[102:105], v[28:29], off offset:320
	global_load_dwordx4 v[106:109], v[6:7], off offset:384
	global_load_dwordx4 v[110:113], v[28:29], off offset:384
	global_load_dwordx4 v[114:117], v[6:7], off offset:448
	global_load_dwordx4 v[118:121], v[28:29], off offset:448
	global_load_dwordx4 v[122:125], v[6:7], off offset:512
	global_load_dwordx4 v[126:129], v[28:29], off offset:512
	global_load_dwordx4 v[130:133], v[6:7], off offset:576
	global_load_dwordx4 v[134:137], v[28:29], off offset:576
	global_load_dwordx4 v[138:141], v[6:7], off offset:640
	global_load_dwordx4 v[142:145], v[28:29], off offset:640
	global_load_dwordx4 v[146:149], v[6:7], off offset:704
	global_load_dwordx4 v[150:153], v[28:29], off offset:704
	global_load_dwordx4 v[154:157], v[6:7], off offset:768
	global_load_dwordx4 v[158:161], v[28:29], off offset:768
	global_load_dwordx4 v[162:165], v[6:7], off offset:832
	global_load_dwordx4 v[166:169], v[28:29], off offset:832
	global_load_dwordx4 v[170:173], v[6:7], off offset:896
	global_load_dwordx4 v[174:177], v[28:29], off offset:896
	global_load_dwordx4 v[178:181], v[6:7], off offset:960
	global_load_dwordx4 v[182:185], v[28:29], off offset:960
	s_waitcnt vmcnt(30)
	v_mfma_f32_16x16x32_bf16 v[0:3], v[58:61], v[62:65], v[0:3]
	global_load_dwordx4 v[58:61], v[6:7], off offset:1024
	global_load_dwordx4 v[62:65], v[28:29], off offset:1024
	s_waitcnt vmcnt(30)
	v_mfma_f32_16x16x32_bf16 v[0:3], v[66:69], v[70:73], v[0:3]
	global_load_dwordx4 v[66:69], v[6:7], off offset:1088
	global_load_dwordx4 v[70:73], v[28:29], off offset:1088
	s_waitcnt vmcnt(30)
	v_mfma_f32_16x16x32_bf16 v[0:3], v[74:77], v[78:81], v[0:3]
	global_load_dwordx4 v[74:77], v[6:7], off offset:1152
	global_load_dwordx4 v[78:81], v[28:29], off offset:1152
	s_waitcnt vmcnt(30)
	v_mfma_f32_16x16x32_bf16 v[0:3], v[82:85], v[86:89], v[0:3]
	global_load_dwordx4 v[82:85], v[6:7], off offset:1216
	global_load_dwordx4 v[86:89], v[28:29], off offset:1216
	s_waitcnt vmcnt(30)
	v_mfma_f32_16x16x32_bf16 v[0:3], v[90:93], v[94:97], v[0:3]
	global_load_dwordx4 v[90:93], v[6:7], off offset:1280
	global_load_dwordx4 v[94:97], v[28:29], off offset:1280
	s_waitcnt vmcnt(30)
	v_mfma_f32_16x16x32_bf16 v[0:3], v[98:101], v[102:105], v[0:3]
	global_load_dwordx4 v[98:101], v[6:7], off offset:1344
	global_load_dwordx4 v[102:105], v[28:29], off offset:1344
	s_waitcnt vmcnt(30)
	v_mfma_f32_16x16x32_bf16 v[0:3], v[106:109], v[110:113], v[0:3]
	global_load_dwordx4 v[106:109], v[6:7], off offset:1408
	global_load_dwordx4 v[110:113], v[28:29], off offset:1408
	s_waitcnt vmcnt(30)
	v_mfma_f32_16x16x32_bf16 v[0:3], v[114:117], v[118:121], v[0:3]
	global_load_dwordx4 v[114:117], v[6:7], off offset:1472
	global_load_dwordx4 v[118:121], v[28:29], off offset:1472
	s_waitcnt vmcnt(30)
	v_mfma_f32_16x16x32_bf16 v[0:3], v[122:125], v[126:129], v[0:3]
	global_load_dwordx4 v[122:125], v[6:7], off offset:1536
	global_load_dwordx4 v[126:129], v[28:29], off offset:1536
	s_waitcnt vmcnt(30)
	v_mfma_f32_16x16x32_bf16 v[0:3], v[130:133], v[134:137], v[0:3]
	global_load_dwordx4 v[130:133], v[6:7], off offset:1600
	global_load_dwordx4 v[134:137], v[28:29], off offset:1600
	s_waitcnt vmcnt(30)
	v_mfma_f32_16x16x32_bf16 v[0:3], v[138:141], v[142:145], v[0:3]
	global_load_dwordx4 v[138:141], v[6:7], off offset:1664
	global_load_dwordx4 v[142:145], v[28:29], off offset:1664
	s_waitcnt vmcnt(30)
	v_mfma_f32_16x16x32_bf16 v[0:3], v[146:149], v[150:153], v[0:3]
	global_load_dwordx4 v[146:149], v[6:7], off offset:1728
	global_load_dwordx4 v[150:153], v[28:29], off offset:1728
	s_waitcnt vmcnt(30)
	v_mfma_f32_16x16x32_bf16 v[0:3], v[154:157], v[158:161], v[0:3]
	global_load_dwordx4 v[154:157], v[6:7], off offset:1792
	global_load_dwordx4 v[158:161], v[28:29], off offset:1792
	s_waitcnt vmcnt(30)
	v_mfma_f32_16x16x32_bf16 v[0:3], v[162:165], v[166:169], v[0:3]
	global_load_dwordx4 v[162:165], v[6:7], off offset:1856
	global_load_dwordx4 v[166:169], v[28:29], off offset:1856
	s_waitcnt vmcnt(30)
	v_mfma_f32_16x16x32_bf16 v[0:3], v[170:173], v[174:177], v[0:3]
	global_load_dwordx4 v[170:173], v[6:7], off offset:1920
	global_load_dwordx4 v[174:177], v[28:29], off offset:1920
	s_waitcnt vmcnt(30)
; __device__ __forceinline__ void fl_phase(const bf16* H, const bf16* Wfl, const float* bfv, const float* rowss, const float* biasp, float* logf, int G) {
;     ...
;         for (int ks = 0; ks < 32; ++ks) { const bf16x8 a = *(const bf16x8*)(ap + 32 * ks), b = *(const bf16x8*)(bp + 32 * ks);
;             acc = __builtin_amdgcn_mfma_f32_16x16x32_bf16(a, b, acc, 0, 0, 0); }
;         const int row = 16 * rb + 4 * g, bb = row >> 13, t = row & 8191; const float bias = bfv[li] + biasp[bb * 4352 + 4096 + li];
;         const f32x4 rq = *(const f32x4*)(rowss + row);
;         f32x4 o;
; #pragma unroll
;         for (int r = 0; r < 4; ++r) { const float z = acc[r] * __builtin_amdgcn_rsqf(rq[r] * (1.0f / 1024.0f) + EPSN) + bias; o[r] = fminf(z, 0.f) - log1pf(__expf(-fabsf(z))); }
	v_mfma_f32_16x16x32_bf16 v[0:3], v[178:181], v[182:185], v[0:3]
	global_load_dwordx4 v[178:181], v[6:7], off offset:1984
	global_load_dwordx4 v[182:185], v[28:29], off offset:1984
	s_waitcnt vmcnt(30)
	v_mfma_f32_16x16x32_bf16 v[0:3], v[58:61], v[62:65], v[0:3]
	s_waitcnt vmcnt(28)
	v_mfma_f32_16x16x32_bf16 v[0:3], v[66:69], v[70:73], v[0:3]
	s_waitcnt vmcnt(26)
	v_mfma_f32_16x16x32_bf16 v[0:3], v[74:77], v[78:81], v[0:3]
	s_waitcnt vmcnt(24)
	v_mfma_f32_16x16x32_bf16 v[0:3], v[82:85], v[86:89], v[0:3]
	s_waitcnt vmcnt(22)
	v_mfma_f32_16x16x32_bf16 v[0:3], v[90:93], v[94:97], v[0:3]
	s_waitcnt vmcnt(20)
	v_mfma_f32_16x16x32_bf16 v[0:3], v[98:101], v[102:105], v[0:3]
	s_waitcnt vmcnt(18)
	v_mfma_f32_16x16x32_bf16 v[0:3], v[106:109], v[110:113], v[0:3]
	s_waitcnt vmcnt(16)
	v_mfma_f32_16x16x32_bf16 v[0:3], v[114:117], v[118:121], v[0:3]
	s_waitcnt vmcnt(14)
	v_mfma_f32_16x16x32_bf16 v[0:3], v[122:125], v[126:129], v[0:3]
	s_waitcnt vmcnt(12)
	v_mfma_f32_16x16x32_bf16 v[0:3], v[130:133], v[134:137], v[0:3]
	s_waitcnt vmcnt(10)
	v_mfma_f32_16x16x32_bf16 v[0:3], v[138:141], v[142:145], v[0:3]
	s_waitcnt vmcnt(8)
	v_mfma_f32_16x16x32_bf16 v[0:3], v[146:149], v[150:153], v[0:3]
	s_waitcnt vmcnt(6)
	v_mfma_f32_16x16x32_bf16 v[0:3], v[154:157], v[158:161], v[0:3]
	s_waitcnt vmcnt(4)
	v_mfma_f32_16x16x32_bf16 v[0:3], v[162:165], v[166:169], v[0:3]
	s_waitcnt vmcnt(2)
	v_mfma_f32_16x16x32_bf16 v[0:3], v[170:173], v[174:177], v[0:3]
	s_waitcnt vmcnt(0)
	v_mfma_f32_16x16x32_bf16 v[0:3], v[178:181], v[182:185], v[0:3]
	v_ashrrev_i32_e32 v15, 9, v44
	v_lshlrev_b32_e32 v8, 4, v44
	s_movk_i32 s14, 0x1ffc
	v_add_u32_e32 v44, s4, v44
	v_add_u32_e32 v14, s5, v14
	v_add_f32_e32 v52, v186, v187
	v_mov_b32_e32 v4, v188
	v_mov_b32_e32 v5, v189
	v_mov_b32_e32 v6, v190
	v_mov_b32_e32 v7, v191
	v_fmamk_f32 v4, v4, 0x3a800000, v48
	v_rsq_f32_e32 v4, v4
	v_fmamk_f32 v5, v5, 0x3a800000, v48
	v_rsq_f32_e32 v5, v5
	v_fma_f32 v4, v0, v4, v52
	v_min_f32_e32 v0, 0, v4
	v_mul_f32_e64 v4, |v4|, s47
	v_exp_f32_e32 v53, v4
	v_fma_f32 v5, v1, v5, v52
	v_min_f32_e32 v1, 0, v5
	v_mul_f32_e64 v5, |v5|, s47
	v_add_f32_e32 v4, 1.0, v53
	v_add_f32_e32 v20, -1.0, v4
	v_sub_f32_e32 v21, v20, v4
	v_add_f32_e32 v21, 1.0, v21
	v_sub_f32_e32 v20, v53, v20
	v_add_f32_e32 v22, v20, v21
	v_frexp_mant_f32_e32 v20, v4
	v_exp_f32_e32 v54, v5
	v_cmp_gt_f32_e32 vcc, s49, v20
	v_cvt_f64_f32_e32 v[20:21], v4
	v_frexp_exp_i32_f64_e32 v20, v[20:21]
	v_subbrev_co_u32_e32 v20, vcc, 0, v20, vcc
	v_sub_u32_e32 v21, 0, v20
	v_add_f32_e32 v5, 1.0, v54
	v_ldexp_f32 v4, v4, v21
	v_ldexp_f32 v22, v22, v21
	v_add_f32_e32 v21, -1.0, v5
	v_sub_f32_e32 v23, v21, v5
	v_add_f32_e32 v23, 1.0, v23
	v_sub_f32_e32 v21, v54, v21
	v_add_f32_e32 v21, v21, v23
	v_frexp_mant_f32_e32 v23, v5
	v_cvt_f64_f32_e32 v[24:25], v5
	v_cmp_gt_f32_e32 vcc, s49, v23
	v_frexp_exp_i32_f64_e32 v23, v[24:25]
	v_cmp_lt_f32_e64 s[36:37], |v54|, s53
	v_subbrev_co_u32_e32 v40, vcc, 0, v23, vcc
	v_sub_u32_e32 v23, 0, v40
	v_ldexp_f32 v5, v5, v23
	v_pk_add_f32 v[24:25], v[4:5], 1.0 op_sel_hi:[1,0]
	v_ldexp_f32 v23, v21, v23
	v_pk_add_f32 v[26:27], v[24:25], -1.0 op_sel_hi:[1,0]
	v_pk_add_f32 v[32:33], v[4:5], -1.0 op_sel_hi:[1,0]
	v_pk_add_f32 v[26:27], v[4:5], v[26:27] neg_lo:[0,1] neg_hi:[0,1]
	v_pk_add_f32 v[34:35], v[32:33], 1.0 op_sel_hi:[1,0]
	v_pk_add_f32 v[26:27], v[22:23], v[26:27]
	v_pk_add_f32 v[4:5], v[4:5], v[34:35] neg_lo:[0,1] neg_hi:[0,1]
	v_pk_add_f32 v[28:29], v[24:25], v[26:27]
	v_pk_add_f32 v[4:5], v[22:23], v[4:5]
	v_rcp_f32_e32 v30, v28
	v_rcp_f32_e32 v31, v29
	v_pk_add_f32 v[22:23], v[32:33], v[4:5]
	v_pk_add_f32 v[24:25], v[28:29], v[24:25] neg_lo:[0,1] neg_hi:[0,1]
	v_pk_add_f32 v[32:33], v[22:23], v[32:33] neg_lo:[0,1] neg_hi:[0,1]
	v_pk_add_f32 v[24:25], v[26:27], v[24:25] neg_lo:[0,1] neg_hi:[0,1]
	v_pk_mul_f32 v[26:27], v[22:23], v[30:31]
	v_pk_add_f32 v[4:5], v[4:5], v[32:33] neg_lo:[0,1] neg_hi:[0,1]
	v_pk_mul_f32 v[32:33], v[28:29], v[26:27]
	v_cmp_neq_f32_e32 vcc, s51, v53
	v_pk_fma_f32 v[34:35], v[26:27], v[28:29], v[32:33] neg_lo:[0,0,1] neg_hi:[0,0,1]
	s_nop 0
	v_pk_fma_f32 v[34:35], v[26:27], v[24:25], v[34:35]
	s_nop 0
	v_pk_add_f32 v[36:37], v[32:33], v[34:35]
	s_nop 0
	v_pk_add_f32 v[38:39], v[22:23], v[36:37] neg_lo:[0,1] neg_hi:[0,1]
	v_pk_add_f32 v[32:33], v[36:37], v[32:33] neg_lo:[0,1] neg_hi:[0,1]
	v_pk_add_f32 v[22:23], v[22:23], v[38:39] neg_lo:[0,1] neg_hi:[0,1]
	s_nop 0
	v_pk_add_f32 v[22:23], v[22:23], v[36:37] neg_lo:[0,1] neg_hi:[0,1]
	s_nop 0
	v_pk_add_f32 v[4:5], v[4:5], v[22:23]
	v_pk_add_f32 v[22:23], v[32:33], v[34:35] neg_lo:[0,1] neg_hi:[0,1]
	s_nop 0
	v_pk_add_f32 v[4:5], v[22:23], v[4:5]
	s_nop 0
	v_pk_add_f32 v[22:23], v[38:39], v[4:5]
	s_nop 0
	v_pk_mul_f32 v[32:33], v[30:31], v[22:23]
	s_nop 0
	v_pk_mul_f32 v[34:35], v[28:29], v[32:33]
	s_nop 0
	v_pk_fma_f32 v[28:29], v[32:33], v[28:29], v[34:35] neg_lo:[0,0,1] neg_hi:[0,0,1]
	s_nop 0
	v_pk_fma_f32 v[24:25], v[32:33], v[24:25], v[28:29]
	v_pk_add_f32 v[28:29], v[38:39], v[22:23] neg_lo:[0,1] neg_hi:[0,1]
	s_nop 0
	v_pk_add_f32 v[4:5], v[4:5], v[28:29]
	v_pk_add_f32 v[28:29], v[34:35], v[24:25]
	s_nop 0
	v_pk_add_f32 v[36:37], v[22:23], v[28:29] neg_lo:[0,1] neg_hi:[0,1]
	v_pk_add_f32 v[34:35], v[28:29], v[34:35] neg_lo:[0,1] neg_hi:[0,1]
	v_pk_add_f32 v[22:23], v[22:23], v[36:37] neg_lo:[0,1] neg_hi:[0,1]
	s_nop 0
	v_pk_add_f32 v[22:23], v[22:23], v[28:29] neg_lo:[0,1] neg_hi:[0,1]
	s_nop 0
	v_pk_add_f32 v[4:5], v[4:5], v[22:23]
	v_pk_add_f32 v[22:23], v[34:35], v[24:25] neg_lo:[0,1] neg_hi:[0,1]
	s_nop 0
	v_pk_add_f32 v[4:5], v[22:23], v[4:5]
	v_pk_add_f32 v[22:23], v[26:27], v[32:33]
	v_pk_add_f32 v[4:5], v[36:37], v[4:5]
; __device__ __forceinline__ void fl_phase(const bf16* H, const bf16* Wfl, const float* bfv, const float* rowss, const float* biasp, float* logf, int G) {
;     ...
;         for (int r = 0; r < 4; ++r) { const float z = acc[r] * __builtin_amdgcn_rsqf(rq[r] * (1.0f / 1024.0f) + EPSN) + bias; o[r] = fminf(z, 0.f) - log1pf(__expf(-fabsf(z))); }
	v_pk_add_f32 v[24:25], v[22:23], v[26:27] neg_lo:[0,1] neg_hi:[0,1]
	v_pk_mul_f32 v[4:5], v[30:31], v[4:5]
	v_pk_add_f32 v[24:25], v[32:33], v[24:25] neg_lo:[0,1] neg_hi:[0,1]
	s_nop 0
	v_pk_add_f32 v[4:5], v[24:25], v[4:5]
	s_nop 0
	v_pk_add_f32 v[24:25], v[22:23], v[4:5]
	s_nop 0
	v_pk_add_f32 v[22:23], v[24:25], v[22:23] neg_lo:[0,1] neg_hi:[0,1]
	v_pk_mul_f32 v[32:33], v[24:25], v[24:25]
	v_pk_add_f32 v[22:23], v[4:5], v[22:23] neg_lo:[0,1] neg_hi:[0,1]
	v_ldexp_f32 v28, v24, 1
	v_ldexp_f32 v26, v22, 1
	v_pk_fma_f32 v[4:5], v[32:33], s[46:47], v[18:19] op_sel_hi:[1,0,0]
	v_ldexp_f32 v29, v25, 1
	v_ldexp_f32 v31, v23, 1
	v_pk_mul_f32 v[22:23], v[24:25], v[32:33]
	v_cvt_f32_i32_e32 v25, v40
	v_cvt_f32_i32_e32 v24, v20
	v_pk_fma_f32 v[4:5], v[32:33], v[4:5], s[48:49] op_sel_hi:[1,1,0]
	v_mov_b32_e32 v27, v31
	v_pk_mul_f32 v[32:33], v[22:23], v[4:5]
	v_pk_mul_f32 v[20:21], v[24:25], s[50:51] op_sel_hi:[1,0]
	v_pk_add_f32 v[4:5], v[28:29], v[32:33]
	v_pk_fma_f32 v[22:23], v[24:25], s[50:51], v[20:21] op_sel_hi:[1,0,1] neg_lo:[0,0,1] neg_hi:[0,0,1]
	v_pk_add_f32 v[28:29], v[4:5], v[28:29] neg_lo:[0,1] neg_hi:[0,1]
	v_pk_fma_f32 v[22:23], v[24:25], s[52:53], v[22:23] op_sel_hi:[1,0,1]
	v_pk_add_f32 v[34:35], v[32:33], v[28:29] neg_lo:[0,1] neg_hi:[0,1]
	v_mov_b32_e32 v28, v20
	v_pk_add_f32 v[32:33], v[26:27], v[34:35]
	v_mov_b32_e32 v29, v35
	v_mov_b32_e32 v30, v22
	v_mov_b32_e32 v27, v33
	v_mov_b32_e32 v35, v5
	v_pk_add_f32 v[24:25], v[20:21], v[22:23]
	v_pk_add_f32 v[28:29], v[28:29], v[30:31]
	v_pk_add_f32 v[30:31], v[26:27], v[34:35]
	v_pk_add_f32 v[34:35], v[4:5], v[32:33]
	v_mov_b32_e32 v42, v4
	v_pk_add_f32 v[26:27], v[24:25], v[34:35]
	v_mov_b32_e32 v40, v34
	v_mov_b32_e32 v41, v27
	v_mov_b32_e32 v43, v25
	v_pk_add_f32 v[40:41], v[40:41], v[42:43] neg_lo:[0,1] neg_hi:[0,1]
	v_mov_b32_e32 v36, v26
	v_mov_b32_e32 v37, v25
	v_mov_b32_e32 v38, v24
	v_mov_b32_e32 v39, v21
	v_mov_b32_e32 v42, v24
	v_mov_b32_e32 v43, v27
	v_mov_b32_e32 v21, v41
	v_pk_add_f32 v[36:37], v[36:37], v[38:39] neg_lo:[0,1] neg_hi:[0,1]
	v_mov_b32_e32 v38, v34
	v_mov_b32_e32 v39, v23
	v_pk_add_f32 v[20:21], v[42:43], v[20:21] neg_lo:[0,1] neg_hi:[0,1]
	v_pk_add_f32 v[38:39], v[38:39], v[36:37] neg_lo:[0,1] neg_hi:[0,1]
	v_mov_b32_e32 v42, v20
	v_mov_b32_e32 v43, v37
	v_mov_b32_e32 v56, v26
	v_mov_b32_e32 v57, v35
	v_mov_b32_e32 v37, v5
	v_pk_add_f32 v[42:43], v[22:23], v[42:43] neg_lo:[0,1] neg_hi:[0,1]
	v_pk_add_f32 v[36:37], v[56:57], v[36:37] neg_lo:[0,1] neg_hi:[0,1]
	v_mov_b32_e32 v23, v25
	v_pk_add_f32 v[28:29], v[28:29], v[36:37] neg_lo:[0,1] neg_hi:[0,1]
	v_pk_add_f32 v[20:21], v[22:23], v[20:21] neg_lo:[0,1] neg_hi:[0,1]
	v_pk_add_f32 v[22:23], v[30:31], v[40:41] neg_lo:[0,1] neg_hi:[0,1]
	v_pk_add_f32 v[30:31], v[38:39], v[28:29]
	v_pk_add_f32 v[24:25], v[22:23], v[20:21]
	v_mov_b32_e32 v21, v39
	v_mov_b32_e32 v23, v29
	v_pk_add_f32 v[22:23], v[20:21], v[22:23]
	v_pk_add_f32 v[4:5], v[34:35], v[4:5] neg_lo:[0,1] neg_hi:[0,1]
	v_pk_add_f32 v[22:23], v[22:23], v[42:43] neg_lo:[0,1] neg_hi:[0,1]
	v_mov_b32_e32 v28, v24
	v_mov_b32_e32 v29, v31
	v_pk_add_f32 v[4:5], v[32:33], v[4:5] neg_lo:[0,1] neg_hi:[0,1]
	v_pk_add_f32 v[28:29], v[28:29], v[22:23] neg_lo:[0,1] neg_hi:[0,1]
	v_pk_add_f32 v[4:5], v[4:5], v[22:23] neg_lo:[0,1] neg_hi:[0,1]
	v_pk_add_f32 v[20:21], v[20:21], v[28:29] neg_lo:[0,1] neg_hi:[0,1]
	s_nop 0
	v_pk_add_f32 v[4:5], v[4:5], v[20:21]
	v_pk_add_f32 v[20:21], v[30:31], v[24:25]
	s_nop 0
	v_pk_add_f32 v[22:23], v[26:27], v[20:21]
	s_nop 0
	v_pk_add_f32 v[24:25], v[22:23], v[26:27] neg_lo:[0,1] neg_hi:[0,1]
	s_nop 0
	v_pk_add_f32 v[20:21], v[20:21], v[24:25] neg_lo:[0,1] neg_hi:[0,1]
	s_nop 0
	v_pk_add_f32 v[4:5], v[4:5], v[20:21]
	s_nop 0
	v_pk_add_f32 v[4:5], v[22:23], v[4:5]
	s_nop 0
	v_cndmask_b32_e32 v4, v49, v4, vcc
	v_cmp_neq_f32_e32 vcc, s51, v54
	s_nop 1
	v_cndmask_b32_e32 v5, v49, v5, vcc
	v_cmp_ngt_f32_e32 vcc, -1.0, v54
	s_nop 1
	v_cndmask_b32_e32 v5, v50, v5, vcc
	v_cmp_ngt_f32_e32 vcc, -1.0, v53
	s_nop 1
	v_cndmask_b32_e32 v4, v50, v4, vcc
	v_cmp_neq_f32_e32 vcc, -1.0, v53
	s_nop 1
	v_cndmask_b32_e32 v4, v51, v4, vcc
	v_cmp_neq_f32_e32 vcc, -1.0, v54
	s_nop 1
	v_cndmask_b32_e32 v5, v51, v5, vcc
	v_cmp_lt_f32_e64 vcc, |v53|, s53
	v_cndmask_b32_e64 v5, v5, v54, s[36:37]
	s_nop 0
	v_cndmask_b32_e32 v4, v4, v53, vcc
	v_pk_add_f32 v[0:1], v[0:1], v[4:5] neg_lo:[0,1] neg_hi:[0,1]
	v_fmamk_f32 v4, v6, 0x3a800000, v48
	v_rsq_f32_e32 v4, v4
	s_nop 0
	v_fma_f32 v4, v2, v4, v52
	v_min_f32_e32 v2, 0, v4
	v_mul_f32_e64 v4, |v4|, s47
	v_exp_f32_e32 v53, v4
	s_nop 0
	v_add_f32_e32 v6, 1.0, v53
	v_add_f32_e32 v4, -1.0, v6
	v_sub_f32_e32 v5, v4, v6
	v_add_f32_e32 v5, 1.0, v5
	v_sub_f32_e32 v4, v53, v4
	v_add_f32_e32 v20, v4, v5
	v_frexp_mant_f32_e32 v4, v6
	v_cmp_gt_f32_e32 vcc, s49, v4
	v_cvt_f64_f32_e32 v[4:5], v6
	v_frexp_exp_i32_f64_e32 v4, v[4:5]
	v_subbrev_co_u32_e32 v36, vcc, 0, v4, vcc
	v_sub_u32_e32 v5, 0, v36
	v_ldexp_f32 v4, v6, v5
	v_ldexp_f32 v6, v20, v5
	v_fmamk_f32 v5, v7, 0x3a800000, v48
	v_rsq_f32_e32 v5, v5
	s_nop 0
	v_fmac_f32_e32 v52, v3, v5
	v_mul_f32_e64 v5, |v52|, s47
	v_min_f32_e32 v3, 0, v52
	v_exp_f32_e32 v52, v5
	s_nop 0
	v_add_f32_e32 v5, 1.0, v52
	v_add_f32_e32 v7, -1.0, v5
	v_sub_f32_e32 v20, v7, v5
	v_add_f32_e32 v20, 1.0, v20
	v_sub_f32_e32 v7, v52, v7
	v_add_f32_e32 v7, v7, v20
	v_frexp_mant_f32_e32 v20, v5
	v_cmp_gt_f32_e32 vcc, s49, v20
	v_cvt_f64_f32_e32 v[20:21], v5
	v_frexp_exp_i32_f64_e32 v20, v[20:21]
	v_subbrev_co_u32_e32 v37, vcc, 0, v20, vcc
	v_sub_u32_e32 v20, 0, v37
	v_ldexp_f32 v5, v5, v20
	v_ldexp_f32 v7, v7, v20
	v_pk_add_f32 v[20:21], v[4:5], 1.0 op_sel_hi:[1,0]
	v_pk_add_f32 v[28:29], v[4:5], -1.0 op_sel_hi:[1,0]
; __device__ __forceinline__ void fl_phase(const bf16* H, const bf16* Wfl, const float* bfv, const float* rowss, const float* biasp, float* logf, int G) {
;     ...
;         for (int r = 0; r < 4; ++r) { const float z = acc[r] * __builtin_amdgcn_rsqf(rq[r] * (1.0f / 1024.0f) + EPSN) + bias; o[r] = fminf(z, 0.f) - log1pf(__expf(-fabsf(z))); }
	v_pk_add_f32 v[22:23], v[20:21], -1.0 op_sel_hi:[1,0]
	v_pk_add_f32 v[30:31], v[28:29], 1.0 op_sel_hi:[1,0]
	v_pk_add_f32 v[22:23], v[4:5], v[22:23] neg_lo:[0,1] neg_hi:[0,1]
	v_pk_add_f32 v[4:5], v[4:5], v[30:31] neg_lo:[0,1] neg_hi:[0,1]
	v_pk_add_f32 v[22:23], v[6:7], v[22:23]
	v_pk_add_f32 v[4:5], v[6:7], v[4:5]
	v_pk_add_f32 v[24:25], v[20:21], v[22:23]
	v_pk_add_f32 v[6:7], v[28:29], v[4:5]
	v_rcp_f32_e32 v26, v24
	v_rcp_f32_e32 v27, v25
	v_pk_add_f32 v[20:21], v[24:25], v[20:21] neg_lo:[0,1] neg_hi:[0,1]
	v_pk_add_f32 v[28:29], v[6:7], v[28:29] neg_lo:[0,1] neg_hi:[0,1]
	v_pk_add_f32 v[20:21], v[22:23], v[20:21] neg_lo:[0,1] neg_hi:[0,1]
	v_pk_mul_f32 v[22:23], v[6:7], v[26:27]
	v_pk_add_f32 v[4:5], v[4:5], v[28:29] neg_lo:[0,1] neg_hi:[0,1]
	v_pk_mul_f32 v[28:29], v[24:25], v[22:23]
	v_cmp_neq_f32_e32 vcc, s51, v53
	v_pk_fma_f32 v[30:31], v[22:23], v[24:25], v[28:29] neg_lo:[0,0,1] neg_hi:[0,0,1]
	v_cmp_lt_f32_e64 s[36:37], |v52|, s53
	v_pk_fma_f32 v[30:31], v[22:23], v[20:21], v[30:31]
	s_nop 0
	v_pk_add_f32 v[32:33], v[28:29], v[30:31]
	s_nop 0
	v_pk_add_f32 v[34:35], v[6:7], v[32:33] neg_lo:[0,1] neg_hi:[0,1]
	v_pk_add_f32 v[28:29], v[32:33], v[28:29] neg_lo:[0,1] neg_hi:[0,1]
	v_pk_add_f32 v[6:7], v[6:7], v[34:35] neg_lo:[0,1] neg_hi:[0,1]
	s_nop 0
	v_pk_add_f32 v[6:7], v[6:7], v[32:33] neg_lo:[0,1] neg_hi:[0,1]
	s_nop 0
	v_pk_add_f32 v[4:5], v[4:5], v[6:7]
	v_pk_add_f32 v[6:7], v[28:29], v[30:31] neg_lo:[0,1] neg_hi:[0,1]
	s_nop 0
	v_pk_add_f32 v[4:5], v[6:7], v[4:5]
	s_nop 0
	v_pk_add_f32 v[6:7], v[34:35], v[4:5]
	s_nop 0
	v_pk_mul_f32 v[28:29], v[26:27], v[6:7]
	s_nop 0
	v_pk_mul_f32 v[30:31], v[24:25], v[28:29]
	s_nop 0
	v_pk_fma_f32 v[24:25], v[28:29], v[24:25], v[30:31] neg_lo:[0,0,1] neg_hi:[0,0,1]
	s_nop 0
	v_pk_fma_f32 v[20:21], v[28:29], v[20:21], v[24:25]
	v_pk_add_f32 v[24:25], v[34:35], v[6:7] neg_lo:[0,1] neg_hi:[0,1]
	s_nop 0
	v_pk_add_f32 v[4:5], v[4:5], v[24:25]
	v_pk_add_f32 v[24:25], v[30:31], v[20:21]
	s_nop 0
	v_pk_add_f32 v[32:33], v[6:7], v[24:25] neg_lo:[0,1] neg_hi:[0,1]
	v_pk_add_f32 v[30:31], v[24:25], v[30:31] neg_lo:[0,1] neg_hi:[0,1]
	v_pk_add_f32 v[6:7], v[6:7], v[32:33] neg_lo:[0,1] neg_hi:[0,1]
	s_nop 0
	v_pk_add_f32 v[6:7], v[6:7], v[24:25] neg_lo:[0,1] neg_hi:[0,1]
	s_nop 0
	v_pk_add_f32 v[4:5], v[4:5], v[6:7]
	v_pk_add_f32 v[6:7], v[30:31], v[20:21] neg_lo:[0,1] neg_hi:[0,1]
	s_nop 0
	v_pk_add_f32 v[4:5], v[6:7], v[4:5]
	v_pk_add_f32 v[6:7], v[22:23], v[28:29]
	v_pk_add_f32 v[4:5], v[32:33], v[4:5]
	v_pk_add_f32 v[20:21], v[6:7], v[22:23] neg_lo:[0,1] neg_hi:[0,1]
	v_pk_mul_f32 v[4:5], v[26:27], v[4:5]
	v_pk_add_f32 v[20:21], v[28:29], v[20:21] neg_lo:[0,1] neg_hi:[0,1]
	s_nop 0
	v_pk_add_f32 v[4:5], v[20:21], v[4:5]
	s_nop 0
	v_pk_add_f32 v[20:21], v[6:7], v[4:5]
	s_nop 0
	v_pk_mul_f32 v[22:23], v[20:21], v[20:21]
	v_pk_add_f32 v[6:7], v[20:21], v[6:7] neg_lo:[0,1] neg_hi:[0,1]
	v_pk_fma_f32 v[24:25], v[22:23], s[46:47], v[18:19] op_sel_hi:[1,0,0]
	v_pk_add_f32 v[4:5], v[4:5], v[6:7] neg_lo:[0,1] neg_hi:[0,1]
	v_ldexp_f32 v6, v20, 1
	v_pk_fma_f32 v[24:25], v[22:23], v[24:25], s[48:49] op_sel_hi:[1,1,0]
	v_ldexp_f32 v7, v21, 1
	v_pk_mul_f32 v[20:21], v[20:21], v[22:23]
	v_cvt_f32_i32_e32 v23, v37
	v_cvt_f32_i32_e32 v22, v36
	v_pk_mul_f32 v[20:21], v[20:21], v[24:25]
	v_ldexp_f32 v27, v5, 1
	v_pk_add_f32 v[24:25], v[6:7], v[20:21]
	v_pk_mul_f32 v[28:29], v[22:23], s[50:51] op_sel_hi:[1,0]
	v_pk_add_f32 v[6:7], v[24:25], v[6:7] neg_lo:[0,1] neg_hi:[0,1]
	v_pk_fma_f32 v[30:31], v[22:23], s[50:51], v[28:29] op_sel_hi:[1,0,1] neg_lo:[0,0,1] neg_hi:[0,0,1]
	v_pk_add_f32 v[6:7], v[20:21], v[6:7] neg_lo:[0,1] neg_hi:[0,1]
; __device__ __forceinline__ void fl_phase(const bf16* H, const bf16* Wfl, const float* bfv, const float* rowss, const float* biasp, float* logf, int G) {
;     ...
;         const int row = 16 * rb + 4 * g, bb = row >> 13, t = row & 8191; const float bias = bfv[li] + biasp[bb * 4352 + 4096 + li];
;         const f32x4 rq = *(const f32x4*)(rowss + row);
;         f32x4 o;
; #pragma unroll
;         for (int r = 0; r < 4; ++r) { const float z = acc[r] * __builtin_amdgcn_rsqf(rq[r] * (1.0f / 1024.0f) + EPSN) + bias; o[r] = fminf(z, 0.f) - log1pf(__expf(-fabsf(z))); }
;         *(f32x4*)(logf + (size_t)(bb * 16 + li) * SEQL + t) = o;
;     }
	v_pk_fma_f32 v[22:23], v[22:23], s[52:53], v[30:31] op_sel_hi:[1,0,1]
	v_ldexp_f32 v4, v4, 1
	v_mov_b32_e32 v20, v28
	v_mov_b32_e32 v21, v7
	v_mov_b32_e32 v26, v22
	v_mov_b32_e32 v5, v27
	v_pk_add_f32 v[20:21], v[20:21], v[26:27]
	v_pk_add_f32 v[26:27], v[4:5], v[6:7]
	v_mov_b32_e32 v7, v25
	v_mov_b32_e32 v5, v27
	v_pk_add_f32 v[30:31], v[28:29], v[22:23]
	v_pk_add_f32 v[4:5], v[4:5], v[6:7]
	v_pk_add_f32 v[6:7], v[24:25], v[26:27]
	v_mov_b32_e32 v40, v24
	v_pk_add_f32 v[32:33], v[30:31], v[6:7]
	v_mov_b32_e32 v38, v6
	v_mov_b32_e32 v39, v33
	v_mov_b32_e32 v41, v31
	v_pk_add_f32 v[38:39], v[38:39], v[40:41] neg_lo:[0,1] neg_hi:[0,1]
	v_mov_b32_e32 v34, v32
	v_mov_b32_e32 v35, v31
	v_mov_b32_e32 v36, v30
	v_mov_b32_e32 v37, v29
	v_mov_b32_e32 v40, v30
	v_mov_b32_e32 v41, v33
	v_mov_b32_e32 v29, v39
	v_pk_add_f32 v[34:35], v[34:35], v[36:37] neg_lo:[0,1] neg_hi:[0,1]
	v_mov_b32_e32 v36, v6
	v_mov_b32_e32 v37, v23
	v_pk_add_f32 v[28:29], v[40:41], v[28:29] neg_lo:[0,1] neg_hi:[0,1]
	v_pk_add_f32 v[36:37], v[36:37], v[34:35] neg_lo:[0,1] neg_hi:[0,1]
	v_mov_b32_e32 v40, v28
	v_mov_b32_e32 v41, v35
	v_mov_b32_e32 v42, v32
	v_mov_b32_e32 v43, v7
	v_mov_b32_e32 v35, v25
	v_pk_add_f32 v[40:41], v[22:23], v[40:41] neg_lo:[0,1] neg_hi:[0,1]
	v_pk_add_f32 v[34:35], v[42:43], v[34:35] neg_lo:[0,1] neg_hi:[0,1]
	v_mov_b32_e32 v23, v31
	v_pk_add_f32 v[20:21], v[20:21], v[34:35] neg_lo:[0,1] neg_hi:[0,1]
	v_pk_add_f32 v[22:23], v[22:23], v[28:29] neg_lo:[0,1] neg_hi:[0,1]
	v_pk_add_f32 v[4:5], v[4:5], v[38:39] neg_lo:[0,1] neg_hi:[0,1]
	v_pk_add_f32 v[6:7], v[6:7], v[24:25] neg_lo:[0,1] neg_hi:[0,1]
	v_pk_add_f32 v[24:25], v[4:5], v[22:23]
	v_mov_b32_e32 v23, v37
	v_mov_b32_e32 v5, v21
	v_pk_add_f32 v[6:7], v[26:27], v[6:7] neg_lo:[0,1] neg_hi:[0,1]
	v_pk_add_f32 v[26:27], v[36:37], v[20:21]
	v_pk_add_f32 v[4:5], v[22:23], v[4:5]
	v_mov_b32_e32 v20, v24
	v_pk_add_f32 v[4:5], v[4:5], v[40:41] neg_lo:[0,1] neg_hi:[0,1]
	v_mov_b32_e32 v21, v27
	v_pk_add_f32 v[20:21], v[20:21], v[4:5] neg_lo:[0,1] neg_hi:[0,1]
	v_pk_add_f32 v[4:5], v[6:7], v[4:5] neg_lo:[0,1] neg_hi:[0,1]
	v_pk_add_f32 v[20:21], v[22:23], v[20:21] neg_lo:[0,1] neg_hi:[0,1]
	v_pk_add_f32 v[6:7], v[26:27], v[24:25]
	v_pk_add_f32 v[4:5], v[4:5], v[20:21]
	v_pk_add_f32 v[20:21], v[32:33], v[6:7]
	s_nop 0
	v_pk_add_f32 v[22:23], v[20:21], v[32:33] neg_lo:[0,1] neg_hi:[0,1]
	s_nop 0
	v_pk_add_f32 v[6:7], v[6:7], v[22:23] neg_lo:[0,1] neg_hi:[0,1]
	s_nop 0
	v_pk_add_f32 v[4:5], v[4:5], v[6:7]
	v_bitop3_b32 v6, v8, s14, v47 bitop3:0xc8
	v_pk_add_f32 v[4:5], v[20:21], v[4:5]
	s_movk_i32 s14, 0x3ff
	v_cndmask_b32_e32 v4, v49, v4, vcc
	v_cmp_neq_f32_e32 vcc, s51, v52
	v_lshlrev_b32_e32 v8, 2, v6
	s_nop 0
	v_cndmask_b32_e32 v5, v49, v5, vcc
	v_cmp_ngt_f32_e32 vcc, -1.0, v52
	s_nop 1
	v_cndmask_b32_e32 v5, v50, v5, vcc
	v_cmp_ngt_f32_e32 vcc, -1.0, v53
	s_nop 1
	v_cndmask_b32_e32 v4, v50, v4, vcc
	v_cmp_neq_f32_e32 vcc, -1.0, v53
	s_nop 1
	v_cndmask_b32_e32 v4, v51, v4, vcc
	v_cmp_neq_f32_e32 vcc, -1.0, v52
	s_nop 1
	v_cndmask_b32_e32 v5, v51, v5, vcc
	v_cmp_lt_f32_e64 vcc, |v53|, s53
	v_cndmask_b32_e64 v5, v5, v52, s[36:37]
	s_nop 0
	v_cndmask_b32_e32 v4, v4, v53, vcc
	v_pk_add_f32 v[2:3], v[2:3], v[4:5] neg_lo:[0,1] neg_hi:[0,1]
	v_lshl_or_b32 v4, v15, 4, v45
	v_ashrrev_i32_e32 v5, 31, v4
	v_lshlrev_b64 v[4:5], 15, v[4:5]
	v_lshl_add_u64 v[4:5], s[0:1], 0, v[4:5]
	v_cmp_lt_i32_e32 vcc, s14, v44
	v_lshl_add_u64 v[4:5], v[4:5], 0, v[8:9]
	s_or_b64 s[40:41], vcc, s[40:41]
	global_store_dwordx4 v[4:5], v[0:3], off
	s_andn2_b64 exec, exec, s[40:41]
	s_cbranch_execnz .LBB0_619
